# GEMM epilogues: removed 50 leftover lgkmcnt(0) waits (from converted cross-lane hops) that serialised still-asynchronous ds_bpermute results
# speedup vs baseline: 1.0050x; 1.0007x over previous
; __device__ __forceinline__ void load_row_scales(const float* ssp, int row0, int fq, float (&rs)[2][4]) {
;     f32x4 part[2][4];
;     const float* sp = ssp + (size_t)row0 * 16 + 4 * fq;
; #pragma unroll
;     for (int ai = 0; ai < 2; ++ai)
; #pragma unroll
;         for (int m = 0; m < 4; ++m) part[ai][m] = *(const f32x4*)(sp + (size_t)(ai * HALF + m * 16) * 16);
; #pragma unroll
;     for (int ai = 0; ai < 2; ++ai)
; #pragma unroll
;         for (int m = 0; m < 4; ++m) { float t = (part[ai][m][0] + part[ai][m][1]) + (part[ai][m][2] + part[ai][m][3]);
;             t += __shfl_xor(t, 16); t += __shfl_xor(t, 32);
;             rs[ai][m] = 1.0f / sqrtf(t * (1.0f / 1024.0f) + 1e-6f); }
; }
.LBB0_271:
	s_and_b64 vcc, exec, s[6:7]
	s_cbranch_vccnz .LBB0_273
	v_lshlrev_b64 v[130:131], 6, v[172:173]
	v_lshl_add_u64 v[130:131], v[166:167], 0, v[130:131]
	global_load_dwordx4 v[182:185], v[130:131], off
	global_load_dwordx4 v[154:157], v[130:131], off offset:1024
	global_load_dwordx4 v[150:153], v[130:131], off offset:2048
	global_load_dwordx4 v[146:149], v[130:131], off offset:3072
	v_add_co_u32_e32 v130, vcc, 0x2000, v130
	v_and_b32_e32 v175, 64, v229
	s_nop 0
	v_addc_co_u32_e32 v131, vcc, 0, v131, vcc
	v_xor_b32_e32 v0, 16, v229
	v_add_u32_e32 v180, 64, v175
	v_cmp_lt_i32_e32 vcc, v0, v180
	global_load_dwordx4 v[142:145], v[130:131], off
	global_load_dwordx4 v[138:141], v[130:131], off offset:1024
	global_load_dwordx4 v[134:137], v[130:131], off offset:2048
	s_nop 0
	global_load_dwordx4 v[130:133], v[130:131], off offset:3072
	v_cndmask_b32_e32 v0, v229, v0, vcc
	v_lshlrev_b32_e32 v175, 2, v0
	v_xor_b32_e32 v0, 32, v229
	v_cmp_lt_i32_e32 vcc, v0, v180
	s_waitcnt vmcnt(0)
	s_mov_b32 s100, 1
	v_mov_b32_e32 v188, v183
	v_mov_b32_e32 v189, v184
	v_mov_b32_e32 v183, v185
	v_cndmask_b32_e32 v0, v229, v0, vcc
	v_pk_add_f32 v[182:183], v[188:189], v[182:183]
	v_lshlrev_b32_e32 v180, 2, v0
	v_add_f32_e32 v0, v182, v183
	v_mov_b32_e32 v181, v0
	s_nop 1
	v_permlane16_swap_b32_e32 v181, v0
	s_waitcnt lgkmcnt(0)
	v_add_f32_e32 v0, v0, v181
	v_mov_b32_e32 v181, v0
	s_nop 1
	v_permlane32_swap_b32_e32 v181, v0
	v_add_f32_e32 v0, v0, v181
	v_fmamk_f32 v0, v0, 0x3a800000, v230
	v_mov_b32_e32 v182, v155
	v_mov_b32_e32 v183, v156
	v_mov_b32_e32 v155, v157
	v_pk_add_f32 v[154:155], v[182:183], v[154:155]
	v_rsq_f32_e32 v0, v0
	s_nop 0
	v_add_f32_e32 v154, v154, v155
	v_mov_b32_e32 v155, v154
	s_nop 1
	v_permlane16_swap_b32_e32 v155, v154
	v_add_f32_e32 v154, v154, v155
	v_mov_b32_e32 v155, v154
	s_nop 1
	v_permlane32_swap_b32_e32 v155, v154
	v_add_f32_e32 v154, v154, v155
	v_fmamk_f32 v154, v154, 0x3a800000, v230
	v_mov_b32_e32 v156, v151
	v_mov_b32_e32 v157, v152
	v_mov_b32_e32 v151, v153
	v_pk_add_f32 v[150:151], v[156:157], v[150:151]
	v_rsq_f32_e32 v154, v154
	s_nop 0
	v_add_f32_e32 v150, v150, v151
	v_mov_b32_e32 v151, v150
	s_nop 1
	v_permlane16_swap_b32_e32 v151, v150
	v_add_f32_e32 v150, v150, v151
	v_mov_b32_e32 v151, v150
	s_nop 1
	v_permlane32_swap_b32_e32 v151, v150
	v_add_f32_e32 v150, v150, v151
	v_fmamk_f32 v150, v150, 0x3a800000, v230
	v_mov_b32_e32 v152, v147
	v_mov_b32_e32 v153, v148
	v_mov_b32_e32 v147, v149
	v_pk_add_f32 v[146:147], v[152:153], v[146:147]
	v_rsq_f32_e32 v150, v150
	s_nop 0
	v_add_f32_e32 v146, v146, v147
	v_mov_b32_e32 v147, v146
	s_nop 1
	v_permlane16_swap_b32_e32 v147, v146
	v_add_f32_e32 v146, v146, v147
	v_mov_b32_e32 v147, v146
	s_nop 1
	v_permlane32_swap_b32_e32 v147, v146
	v_add_f32_e32 v146, v146, v147
	v_fmamk_f32 v146, v146, 0x3a800000, v230
	v_mov_b32_e32 v148, v143
	v_mov_b32_e32 v149, v144
	v_mov_b32_e32 v143, v145
	v_pk_add_f32 v[142:143], v[148:149], v[142:143]
	v_rsq_f32_e32 v146, v146
	s_nop 0
	v_add_f32_e32 v142, v142, v143
	v_mov_b32_e32 v143, v142
	s_nop 1
	v_permlane16_swap_b32_e32 v143, v142
	v_add_f32_e32 v142, v142, v143
	v_mov_b32_e32 v143, v142
	s_nop 1
	v_permlane32_swap_b32_e32 v143, v142
	v_add_f32_e32 v142, v142, v143
	v_fmamk_f32 v142, v142, 0x3a800000, v230
	v_mov_b32_e32 v144, v139
	v_mov_b32_e32 v145, v140
	v_mov_b32_e32 v139, v141
	v_pk_add_f32 v[138:139], v[144:145], v[138:139]
	v_rsq_f32_e32 v142, v142
	s_nop 0
	v_add_f32_e32 v138, v138, v139
	v_mov_b32_e32 v139, v138
	s_nop 1
	v_permlane16_swap_b32_e32 v139, v138
	v_add_f32_e32 v138, v138, v139
	v_mov_b32_e32 v139, v138
	s_nop 1
	v_permlane32_swap_b32_e32 v139, v138
	v_add_f32_e32 v138, v138, v139
	v_fmamk_f32 v138, v138, 0x3a800000, v230
	v_mov_b32_e32 v140, v135
	v_mov_b32_e32 v141, v136
	v_mov_b32_e32 v135, v137
	v_pk_add_f32 v[134:135], v[140:141], v[134:135]
	v_rsq_f32_e32 v138, v138
	s_nop 0
	v_add_f32_e32 v134, v134, v135
	v_mov_b32_e32 v135, v134
	s_nop 1
	v_permlane16_swap_b32_e32 v135, v134
	v_add_f32_e32 v134, v134, v135
	v_mov_b32_e32 v135, v134
	s_nop 1
	v_permlane32_swap_b32_e32 v135, v134
	v_add_f32_e32 v134, v134, v135
	v_fmamk_f32 v134, v134, 0x3a800000, v230
	v_mov_b32_e32 v136, v131
	v_mov_b32_e32 v137, v132
	v_mov_b32_e32 v131, v133
	v_pk_add_f32 v[130:131], v[136:137], v[130:131]
	v_rsq_f32_e32 v134, v134
	s_nop 0
	v_add_f32_e32 v130, v130, v131
	v_mov_b32_e32 v131, v130
	s_nop 1
	v_permlane16_swap_b32_e32 v131, v130
	v_add_f32_e32 v130, v130, v131
	v_mov_b32_e32 v131, v130
	s_nop 1
	v_permlane32_swap_b32_e32 v131, v130
	s_waitcnt lgkmcnt(0)
	v_add_f32_e32 v130, v130, v131
	v_fmamk_f32 v130, v130, 0x3a800000, v230
	v_rsq_f32_e32 v130, v130
	s_nop 0
	s_branch .LBB0_274

; __device__ __forceinline__ void load_row_scales(const float* ssp, int row0, int fq, float (&rs)[2][4]) {
;     f32x4 part[2][4];
;     const float* sp = ssp + (size_t)row0 * 16 + 4 * fq;
; #pragma unroll
;     for (int ai = 0; ai < 2; ++ai)
; #pragma unroll
;         for (int m = 0; m < 4; ++m) part[ai][m] = *(const f32x4*)(sp + (size_t)(ai * HALF + m * 16) * 16);
; #pragma unroll
;     for (int ai = 0; ai < 2; ++ai)
; #pragma unroll
;         for (int m = 0; m < 4; ++m) { float t = (part[ai][m][0] + part[ai][m][1]) + (part[ai][m][2] + part[ai][m][3]);
;             t += __shfl_xor(t, 16); t += __shfl_xor(t, 32);
;             rs[ai][m] = 1.0f / sqrtf(t * (1.0f / 1024.0f) + 1e-6f); }
; }
;     __device__ __forceinline__ void operator()(f32x4 (&acc)[2][2][4][2], const Unit& u, int wr, int wc, int fr, int fq) const {
;     ...
;             if (ssp) { float rs[2][4]; load_row_scales(ssp, row0, fq, rs);
; #pragma unroll
;                 for (int ai = 0; ai < 2; ++ai)
; #pragma unroll
;                     for (int m = 0; m < 4; ++m)
; #pragma unroll
;                         for (int bj = 0; bj < 2; ++bj)
; #pragma unroll
;                             for (int n = 0; n < 2; ++n) acc[ai][bj][m][n] = acc[ai][bj][m][n] * rs[ai][m];
.LBB0_275:
	s_and_b64 vcc, exec, s[6:7]
	s_cbranch_vccnz .LBB0_277
	v_lshlrev_b64 v[130:131], 6, v[172:173]
	v_lshl_add_u64 v[130:131], v[166:167], 0, v[130:131]
	global_load_dwordx4 v[182:185], v[130:131], off
	global_load_dwordx4 v[154:157], v[130:131], off offset:1024
	global_load_dwordx4 v[150:153], v[130:131], off offset:2048
	global_load_dwordx4 v[146:149], v[130:131], off offset:3072
	v_add_co_u32_e32 v130, vcc, 0x2000, v130
	v_and_b32_e32 v175, 64, v229
	s_nop 0
	v_addc_co_u32_e32 v131, vcc, 0, v131, vcc
	v_xor_b32_e32 v0, 16, v229
	v_add_u32_e32 v180, 64, v175
	v_cmp_lt_i32_e32 vcc, v0, v180
	global_load_dwordx4 v[142:145], v[130:131], off
	global_load_dwordx4 v[138:141], v[130:131], off offset:1024
	global_load_dwordx4 v[134:137], v[130:131], off offset:2048
	s_nop 0
	global_load_dwordx4 v[130:133], v[130:131], off offset:3072
	v_cndmask_b32_e32 v0, v229, v0, vcc
	v_lshlrev_b32_e32 v175, 2, v0
	v_xor_b32_e32 v0, 32, v229
	v_cmp_lt_i32_e32 vcc, v0, v180
	s_waitcnt vmcnt(0)
	s_mov_b32 s100, 1
	v_mov_b32_e32 v188, v183
	v_mov_b32_e32 v189, v184
	v_mov_b32_e32 v183, v185
	v_cndmask_b32_e32 v0, v229, v0, vcc
	v_pk_add_f32 v[182:183], v[188:189], v[182:183]
	v_lshlrev_b32_e32 v180, 2, v0
	v_add_f32_e32 v0, v182, v183
	v_mov_b32_e32 v181, v0
	s_nop 1
	v_permlane16_swap_b32_e32 v181, v0
	s_waitcnt lgkmcnt(0)
	v_add_f32_e32 v0, v0, v181
	v_mov_b32_e32 v181, v0
	s_nop 1
	v_permlane32_swap_b32_e32 v181, v0
	v_add_f32_e32 v0, v0, v181
	v_fmamk_f32 v0, v0, 0x3a800000, v230
	v_mov_b32_e32 v182, v155
	v_mov_b32_e32 v183, v156
	v_mov_b32_e32 v155, v157
	v_pk_add_f32 v[154:155], v[182:183], v[154:155]
	v_rsq_f32_e32 v0, v0
	s_nop 0
	v_add_f32_e32 v154, v154, v155
	v_mov_b32_e32 v155, v154
	s_nop 1
	v_permlane16_swap_b32_e32 v155, v154
	v_pk_mul_f32 v[128:129], v[128:129], v[0:1] op_sel_hi:[1,0]
	v_pk_mul_f32 v[126:127], v[126:127], v[0:1] op_sel_hi:[1,0]
	v_pk_mul_f32 v[96:97], v[96:97], v[0:1] op_sel_hi:[1,0]
	v_pk_mul_f32 v[94:95], v[94:95], v[0:1] op_sel_hi:[1,0]
	v_add_f32_e32 v154, v154, v155
	v_mov_b32_e32 v155, v154
	s_nop 1
	v_permlane32_swap_b32_e32 v155, v154
	v_pk_mul_f32 v[64:65], v[64:65], v[0:1] op_sel_hi:[1,0]
	v_pk_mul_f32 v[62:63], v[62:63], v[0:1] op_sel_hi:[1,0]
	v_pk_mul_f32 v[32:33], v[32:33], v[0:1] op_sel_hi:[1,0]
	v_pk_mul_f32 v[30:31], v[30:31], v[0:1] op_sel_hi:[1,0]
	v_add_f32_e32 v154, v154, v155
	v_fmamk_f32 v154, v154, 0x3a800000, v230
	v_mov_b32_e32 v156, v151
	v_mov_b32_e32 v157, v152
	v_mov_b32_e32 v151, v153
	v_pk_add_f32 v[150:151], v[156:157], v[150:151]
	v_rsq_f32_e32 v154, v154
	s_nop 0
	v_add_f32_e32 v150, v150, v151
	v_mov_b32_e32 v151, v150
	s_nop 1
	v_permlane16_swap_b32_e32 v151, v150
	v_add_f32_e32 v150, v150, v151
	v_mov_b32_e32 v151, v150
	s_nop 1
	v_permlane32_swap_b32_e32 v151, v150
	v_add_f32_e32 v150, v150, v151
	v_fmamk_f32 v150, v150, 0x3a800000, v230
	v_mov_b32_e32 v152, v147
	v_mov_b32_e32 v153, v148
	v_mov_b32_e32 v147, v149
	v_pk_add_f32 v[146:147], v[152:153], v[146:147]
	v_rsq_f32_e32 v150, v150
	s_nop 0
	v_add_f32_e32 v146, v146, v147
	v_mov_b32_e32 v147, v146
	s_nop 1
	v_permlane16_swap_b32_e32 v147, v146
	v_pk_mul_f32 v[124:125], v[124:125], v[154:155] op_sel_hi:[1,0]
	v_pk_mul_f32 v[122:123], v[122:123], v[154:155] op_sel_hi:[1,0]
	v_pk_mul_f32 v[92:93], v[92:93], v[154:155] op_sel_hi:[1,0]
	v_pk_mul_f32 v[90:91], v[90:91], v[154:155] op_sel_hi:[1,0]
	v_add_f32_e32 v146, v146, v147
	v_mov_b32_e32 v147, v146
	s_nop 1
	v_permlane32_swap_b32_e32 v147, v146
	v_pk_mul_f32 v[60:61], v[60:61], v[154:155] op_sel_hi:[1,0]
	v_pk_mul_f32 v[58:59], v[58:59], v[154:155] op_sel_hi:[1,0]
	v_pk_mul_f32 v[28:29], v[28:29], v[154:155] op_sel_hi:[1,0]
	v_pk_mul_f32 v[26:27], v[26:27], v[154:155] op_sel_hi:[1,0]
	v_add_f32_e32 v146, v146, v147
	v_fmamk_f32 v146, v146, 0x3a800000, v230
	v_mov_b32_e32 v148, v143
	v_mov_b32_e32 v149, v144
	v_mov_b32_e32 v143, v145
	v_pk_add_f32 v[142:143], v[148:149], v[142:143]
	v_rsq_f32_e32 v146, v146
	s_nop 0
	v_add_f32_e32 v142, v142, v143
	v_mov_b32_e32 v143, v142
	s_nop 1
	v_permlane16_swap_b32_e32 v143, v142
	v_pk_mul_f32 v[120:121], v[120:121], v[150:151] op_sel_hi:[1,0]
	v_pk_mul_f32 v[118:119], v[118:119], v[150:151] op_sel_hi:[1,0]
	v_pk_mul_f32 v[88:89], v[88:89], v[150:151] op_sel_hi:[1,0]
	v_pk_mul_f32 v[86:87], v[86:87], v[150:151] op_sel_hi:[1,0]
; __device__ __forceinline__ void load_row_scales(const float* ssp, int row0, int fq, float (&rs)[2][4]) {
;     f32x4 part[2][4];
;     const float* sp = ssp + (size_t)row0 * 16 + 4 * fq;
; #pragma unroll
;     for (int ai = 0; ai < 2; ++ai)
; #pragma unroll
;         for (int m = 0; m < 4; ++m) part[ai][m] = *(const f32x4*)(sp + (size_t)(ai * HALF + m * 16) * 16);
; #pragma unroll
;     for (int ai = 0; ai < 2; ++ai)
; #pragma unroll
;         for (int m = 0; m < 4; ++m) { float t = (part[ai][m][0] + part[ai][m][1]) + (part[ai][m][2] + part[ai][m][3]);
;             t += __shfl_xor(t, 16); t += __shfl_xor(t, 32);
;             rs[ai][m] = 1.0f / sqrtf(t * (1.0f / 1024.0f) + 1e-6f); }
; }
;     __device__ __forceinline__ void operator()(f32x4 (&acc)[2][2][4][2], const Unit& u, int wr, int wc, int fr, int fq) const {
;     ...
;             if (ssp) { float rs[2][4]; load_row_scales(ssp, row0, fq, rs);
; #pragma unroll
;                 for (int ai = 0; ai < 2; ++ai)
; #pragma unroll
;                     for (int m = 0; m < 4; ++m)
; #pragma unroll
;                         for (int bj = 0; bj < 2; ++bj)
; #pragma unroll
;                             for (int n = 0; n < 2; ++n) acc[ai][bj][m][n] = acc[ai][bj][m][n] * rs[ai][m];
	v_add_f32_e32 v142, v142, v143
	v_mov_b32_e32 v143, v142
	s_nop 1
	v_permlane32_swap_b32_e32 v143, v142
	v_pk_mul_f32 v[56:57], v[56:57], v[150:151] op_sel_hi:[1,0]
	v_pk_mul_f32 v[54:55], v[54:55], v[150:151] op_sel_hi:[1,0]
	v_pk_mul_f32 v[24:25], v[24:25], v[150:151] op_sel_hi:[1,0]
	v_pk_mul_f32 v[22:23], v[22:23], v[150:151] op_sel_hi:[1,0]
	v_add_f32_e32 v142, v142, v143
	v_fmamk_f32 v142, v142, 0x3a800000, v230
	v_mov_b32_e32 v144, v139
	v_mov_b32_e32 v145, v140
	v_mov_b32_e32 v139, v141
	v_pk_add_f32 v[138:139], v[144:145], v[138:139]
	v_rsq_f32_e32 v142, v142
	s_nop 0
	v_add_f32_e32 v138, v138, v139
	v_mov_b32_e32 v139, v138
	s_nop 1
	v_permlane16_swap_b32_e32 v139, v138
	v_pk_mul_f32 v[116:117], v[116:117], v[146:147] op_sel_hi:[1,0]
	v_pk_mul_f32 v[114:115], v[114:115], v[146:147] op_sel_hi:[1,0]
	v_pk_mul_f32 v[84:85], v[84:85], v[146:147] op_sel_hi:[1,0]
	v_pk_mul_f32 v[82:83], v[82:83], v[146:147] op_sel_hi:[1,0]
	v_add_f32_e32 v138, v138, v139
	v_mov_b32_e32 v139, v138
	s_nop 1
	v_permlane32_swap_b32_e32 v139, v138
	v_pk_mul_f32 v[52:53], v[52:53], v[146:147] op_sel_hi:[1,0]
	v_pk_mul_f32 v[50:51], v[50:51], v[146:147] op_sel_hi:[1,0]
	v_pk_mul_f32 v[20:21], v[20:21], v[146:147] op_sel_hi:[1,0]
	v_pk_mul_f32 v[18:19], v[18:19], v[146:147] op_sel_hi:[1,0]
	v_add_f32_e32 v138, v138, v139
	v_fmamk_f32 v138, v138, 0x3a800000, v230
	v_mov_b32_e32 v140, v135
	v_mov_b32_e32 v141, v136
	v_mov_b32_e32 v135, v137
	v_pk_add_f32 v[134:135], v[140:141], v[134:135]
	v_rsq_f32_e32 v138, v138
	s_nop 0
	v_add_f32_e32 v134, v134, v135
	v_mov_b32_e32 v135, v134
	s_nop 1
	v_permlane16_swap_b32_e32 v135, v134
	v_pk_mul_f32 v[112:113], v[112:113], v[142:143] op_sel_hi:[1,0]
	v_pk_mul_f32 v[110:111], v[110:111], v[142:143] op_sel_hi:[1,0]
	v_pk_mul_f32 v[80:81], v[80:81], v[142:143] op_sel_hi:[1,0]
	v_pk_mul_f32 v[78:79], v[78:79], v[142:143] op_sel_hi:[1,0]
	v_add_f32_e32 v134, v134, v135
	v_mov_b32_e32 v135, v134
	s_nop 1
	v_permlane32_swap_b32_e32 v135, v134
	v_pk_mul_f32 v[48:49], v[48:49], v[142:143] op_sel_hi:[1,0]
	v_pk_mul_f32 v[46:47], v[46:47], v[142:143] op_sel_hi:[1,0]
	v_pk_mul_f32 v[16:17], v[16:17], v[142:143] op_sel_hi:[1,0]
	v_pk_mul_f32 v[14:15], v[14:15], v[142:143] op_sel_hi:[1,0]
	v_add_f32_e32 v134, v134, v135
	v_fmamk_f32 v134, v134, 0x3a800000, v230
	v_mov_b32_e32 v136, v131
	v_mov_b32_e32 v137, v132
	v_mov_b32_e32 v131, v133
	v_pk_add_f32 v[130:131], v[136:137], v[130:131]
	v_rsq_f32_e32 v134, v134
	s_nop 0
	v_add_f32_e32 v130, v130, v131
	v_mov_b32_e32 v131, v130
	s_nop 1
	v_permlane16_swap_b32_e32 v131, v130
	v_pk_mul_f32 v[108:109], v[108:109], v[138:139] op_sel_hi:[1,0]
	v_pk_mul_f32 v[106:107], v[106:107], v[138:139] op_sel_hi:[1,0]
	v_pk_mul_f32 v[76:77], v[76:77], v[138:139] op_sel_hi:[1,0]
	v_pk_mul_f32 v[74:75], v[74:75], v[138:139] op_sel_hi:[1,0]
	v_add_f32_e32 v130, v130, v131
	v_mov_b32_e32 v131, v130
	s_nop 1
	v_permlane32_swap_b32_e32 v131, v130
	v_pk_mul_f32 v[44:45], v[44:45], v[138:139] op_sel_hi:[1,0]
	v_pk_mul_f32 v[42:43], v[42:43], v[138:139] op_sel_hi:[1,0]
	v_pk_mul_f32 v[12:13], v[12:13], v[138:139] op_sel_hi:[1,0]
	v_pk_mul_f32 v[10:11], v[10:11], v[138:139] op_sel_hi:[1,0]
	s_waitcnt lgkmcnt(0)
	v_add_f32_e32 v130, v130, v131
	v_fmamk_f32 v130, v130, 0x3a800000, v230
	v_rsq_f32_e32 v130, v130
	s_nop 0
	v_pk_mul_f32 v[104:105], v[104:105], v[134:135] op_sel_hi:[1,0]
	v_pk_mul_f32 v[102:103], v[102:103], v[134:135] op_sel_hi:[1,0]
	v_pk_mul_f32 v[72:73], v[72:73], v[134:135] op_sel_hi:[1,0]
	v_pk_mul_f32 v[70:71], v[70:71], v[134:135] op_sel_hi:[1,0]
	v_pk_mul_f32 v[40:41], v[40:41], v[134:135] op_sel_hi:[1,0]
	v_pk_mul_f32 v[38:39], v[38:39], v[134:135] op_sel_hi:[1,0]
	v_pk_mul_f32 v[8:9], v[8:9], v[134:135] op_sel_hi:[1,0]
	v_pk_mul_f32 v[6:7], v[6:7], v[134:135] op_sel_hi:[1,0]
	v_pk_mul_f32 v[100:101], v[100:101], v[130:131] op_sel_hi:[1,0]
	v_pk_mul_f32 v[98:99], v[98:99], v[130:131] op_sel_hi:[1,0]
	v_pk_mul_f32 v[68:69], v[68:69], v[130:131] op_sel_hi:[1,0]
	v_pk_mul_f32 v[66:67], v[66:67], v[130:131] op_sel_hi:[1,0]
	v_pk_mul_f32 v[36:37], v[36:37], v[130:131] op_sel_hi:[1,0]
	v_pk_mul_f32 v[34:35], v[34:35], v[130:131] op_sel_hi:[1,0]
	v_pk_mul_f32 v[4:5], v[4:5], v[130:131] op_sel_hi:[1,0]
	v_pk_mul_f32 v[2:3], v[2:3], v[130:131] op_sel_hi:[1,0]

; __device__ __forceinline__ unsigned cvt_pk_bf16(float lo, float hi) { unsigned r; asm volatile("v_cvt_pk_bf16_f32 %0, %1, %2" : "=v"(r) : "v"(lo), "v"(hi)); return r; }
; __device__ __forceinline__ void load_row_scales(const float* ssp, int row0, int fq, float (&rs)[2][4]) {
;     f32x4 part[2][4];
;     const float* sp = ssp + (size_t)row0 * 16 + 4 * fq;
; #pragma unroll
;     for (int ai = 0; ai < 2; ++ai)
; #pragma unroll
;         for (int m = 0; m < 4; ++m) part[ai][m] = *(const f32x4*)(sp + (size_t)(ai * HALF + m * 16) * 16);
; #pragma unroll
;     for (int ai = 0; ai < 2; ++ai)
; #pragma unroll
;         for (int m = 0; m < 4; ++m) { float t = (part[ai][m][0] + part[ai][m][1]) + (part[ai][m][2] + part[ai][m][3]);
;             t += __shfl_xor(t, 16); t += __shfl_xor(t, 32);
;             rs[ai][m] = 1.0f / sqrtf(t * (1.0f / 1024.0f) + 1e-6f); }
; }
;     __device__ __forceinline__ void operator()(f32x4 (&acc)[2][2][4][2], const Unit& u, int wr, int wc, int fr, int fq) const {
;     ...
; #pragma unroll
;             for (int ai = 0; ai < 2; ++ai) {
; #pragma unroll
;                 for (int m = 0; m < 4; ++m) { const float rs = rsa[ai][m];
; #pragma unroll
;                     for (int bj = 0; bj < 2; ++bj) { const f32x4 v0 = acc[ai][bj][m][0] * rs, v1 = acc[ai][bj][m][1] * rs;
;                         u32x4 w; w.x = cvt_pk_bf16(v0[0], v0[1]); w.y = cvt_pk_bf16(v0[2], v0[3]); w.z = cvt_pk_bf16(v1[0], v1[1]); w.w = cvt_pk_bf16(v1[2], v1[3]);
;                         *(u32x4*)(rowp + bj * HALF) = w; }
;                     rowp += (size_t)16 * ldr; asm volatile("" : "+v"(rowp) :: "memory"); }
;                 rowp += (size_t)64 * ldr; asm volatile("" : "+v"(rowp)); }
.LBB0_1127:
	v_lshl_add_u32 v130, s13, 8, v173
	v_ashrrev_i32_e32 v131, 31, v130
	v_lshlrev_b64 v[134:135], 11, v[130:131]
	v_lshlrev_b64 v[130:131], 6, v[130:131]
	v_lshl_add_u64 v[130:131], v[164:165], 0, v[130:131]
	global_load_dwordx4 v[180:183], v[130:131], off
	global_load_dwordx4 v[154:157], v[130:131], off offset:1024
	global_load_dwordx4 v[150:153], v[130:131], off offset:2048
	global_load_dwordx4 v[146:149], v[130:131], off offset:3072
	s_movk_i32 s0, 0x2000
	v_add_co_u32_e32 v130, vcc, s0, v130
	v_and_b32_e32 v177, 64, v229
	s_nop 0
	v_addc_co_u32_e32 v131, vcc, 0, v131, vcc
	v_xor_b32_e32 v172, 16, v229
	v_add_u32_e32 v178, 64, v177
	v_cmp_lt_i32_e32 vcc, v172, v178
	v_lshl_or_b32 v132, s12, 8, v175
	v_lshl_add_u64 v[134:135], s[46:47], 0, v[134:135]
	v_cndmask_b32_e32 v172, v229, v172, vcc
	v_lshlrev_b32_e32 v177, 2, v172
	v_xor_b32_e32 v172, 32, v229
	v_cmp_lt_i32_e32 vcc, v172, v178
	v_ashrrev_i32_e32 v133, 31, v132
	v_lshl_add_u64 v[170:171], v[132:133], 1, v[134:135]
	v_cndmask_b32_e32 v172, v229, v172, vcc
	v_lshlrev_b32_e32 v178, 2, v172
	global_load_dwordx4 v[142:145], v[130:131], off
	global_load_dwordx4 v[138:141], v[130:131], off offset:1024
	global_load_dwordx4 v[134:137], v[130:131], off offset:2048
	s_nop 0
	global_load_dwordx4 v[130:133], v[130:131], off offset:3072
	s_mov_b64 s[12:13], 0x8000
	s_waitcnt vmcnt(0)
	s_mov_b32 s100, 1
	v_mov_b32_e32 v184, v181
	v_mov_b32_e32 v185, v182
	v_mov_b32_e32 v181, v183
	v_pk_add_f32 v[180:181], v[184:185], v[180:181]
	s_nop 0
	v_add_f32_e32 v172, v180, v181
	v_mov_b32_e32 v179, v172
	s_nop 1
	v_permlane16_swap_b32_e32 v179, v172
	s_waitcnt lgkmcnt(0)
	v_add_f32_e32 v172, v172, v179
	v_mov_b32_e32 v179, v172
	s_nop 1
	v_permlane32_swap_b32_e32 v179, v172
	v_add_f32_e32 v172, v172, v179
	v_fmamk_f32 v172, v172, 0x3a800000, v230
	v_mov_b32_e32 v180, v155
	v_mov_b32_e32 v181, v156
	v_mov_b32_e32 v155, v157
	v_pk_add_f32 v[154:155], v[180:181], v[154:155]
	v_rsq_f32_e32 v172, v172
	s_nop 0
	v_add_f32_e32 v154, v154, v155
	v_mov_b32_e32 v155, v154
	s_nop 1
	v_permlane16_swap_b32_e32 v155, v154
	v_pk_mul_f32 v[128:129], v[128:129], v[172:173] op_sel_hi:[1,0]
	v_pk_mul_f32 v[126:127], v[126:127], v[172:173] op_sel_hi:[1,0]
	v_pk_mul_f32 v[120:121], v[120:121], v[172:173] op_sel_hi:[1,0]
	v_pk_mul_f32 v[118:119], v[118:119], v[172:173] op_sel_hi:[1,0]
	v_add_f32_e32 v154, v154, v155
	v_mov_b32_e32 v155, v154
	s_nop 1
	v_permlane32_swap_b32_e32 v155, v154
	v_add_f32_e32 v154, v154, v155
	v_fmamk_f32 v154, v154, 0x3a800000, v230
	v_mov_b32_e32 v156, v151
	v_mov_b32_e32 v157, v152
	v_mov_b32_e32 v151, v153
	v_pk_add_f32 v[150:151], v[156:157], v[150:151]
	v_rsq_f32_e32 v154, v154
	s_nop 0
	v_add_f32_e32 v150, v150, v151
	v_mov_b32_e32 v151, v150
	s_nop 1
	v_permlane16_swap_b32_e32 v151, v150
	v_add_f32_e32 v150, v150, v151
	v_mov_b32_e32 v151, v150
	s_nop 1
	v_permlane32_swap_b32_e32 v151, v150
	v_add_f32_e32 v150, v150, v151
	v_fmamk_f32 v150, v150, 0x3a800000, v230
	v_mov_b32_e32 v152, v147
	v_mov_b32_e32 v153, v148
	v_mov_b32_e32 v147, v149
	v_pk_add_f32 v[146:147], v[152:153], v[146:147]
	v_rsq_f32_e32 v150, v150
	s_nop 0
	v_add_f32_e32 v146, v146, v147
	v_mov_b32_e32 v147, v146
	s_nop 1
	v_permlane16_swap_b32_e32 v147, v146
	v_pk_mul_f32 v[114:115], v[114:115], v[154:155] op_sel_hi:[1,0]
	v_pk_mul_f32 v[104:105], v[104:105], v[154:155] op_sel_hi:[1,0]
	v_pk_mul_f32 v[102:103], v[102:103], v[154:155] op_sel_hi:[1,0]
	v_add_f32_e32 v146, v146, v147
	v_mov_b32_e32 v147, v146
	s_nop 1
	v_permlane32_swap_b32_e32 v147, v146
	v_add_f32_e32 v146, v146, v147
	v_fmamk_f32 v146, v146, 0x3a800000, v230
	v_mov_b32_e32 v148, v143
	v_mov_b32_e32 v149, v144
	v_mov_b32_e32 v143, v145
	v_pk_add_f32 v[142:143], v[148:149], v[142:143]
	v_rsq_f32_e32 v146, v146
	s_nop 0
	v_add_f32_e32 v142, v142, v143
	v_mov_b32_e32 v143, v142
	s_nop 1
	v_permlane16_swap_b32_e32 v143, v142
	v_pk_mul_f32 v[98:99], v[98:99], v[150:151] op_sel_hi:[1,0]
	v_pk_mul_f32 v[88:89], v[88:89], v[150:151] op_sel_hi:[1,0]
	v_pk_mul_f32 v[86:87], v[86:87], v[150:151] op_sel_hi:[1,0]
	v_add_f32_e32 v142, v142, v143
	v_mov_b32_e32 v143, v142
	s_nop 1
	v_permlane32_swap_b32_e32 v143, v142
	v_add_f32_e32 v142, v142, v143
	v_fmamk_f32 v142, v142, 0x3a800000, v230
	v_mov_b32_e32 v144, v139
	v_mov_b32_e32 v145, v140
	v_mov_b32_e32 v139, v141
	v_pk_add_f32 v[138:139], v[144:145], v[138:139]
	v_rsq_f32_e32 v142, v142
	s_nop 0
	v_add_f32_e32 v138, v138, v139
	v_mov_b32_e32 v139, v138
	s_nop 1
	v_permlane16_swap_b32_e32 v139, v138
	v_pk_mul_f32 v[82:83], v[82:83], v[146:147] op_sel_hi:[1,0]
	v_pk_mul_f32 v[72:73], v[72:73], v[146:147] op_sel_hi:[1,0]
	v_pk_mul_f32 v[70:71], v[70:71], v[146:147] op_sel_hi:[1,0]
	v_add_f32_e32 v138, v138, v139
	v_mov_b32_e32 v139, v138
	s_nop 1
	v_permlane32_swap_b32_e32 v139, v138
	v_add_f32_e32 v138, v138, v139
	v_fmamk_f32 v138, v138, 0x3a800000, v230
	v_mov_b32_e32 v140, v135
	v_mov_b32_e32 v141, v136
	v_mov_b32_e32 v135, v137
	v_pk_add_f32 v[134:135], v[140:141], v[134:135]
	v_rsq_f32_e32 v138, v138
	s_nop 0
	v_add_f32_e32 v134, v134, v135
	v_mov_b32_e32 v135, v134
	s_nop 1
	v_permlane16_swap_b32_e32 v135, v134
	v_pk_mul_f32 v[64:65], v[64:65], v[142:143] op_sel_hi:[1,0]
	v_pk_mul_f32 v[62:63], v[62:63], v[142:143] op_sel_hi:[1,0]
	v_pk_mul_f32 v[56:57], v[56:57], v[142:143] op_sel_hi:[1,0]
	v_pk_mul_f32 v[54:55], v[54:55], v[142:143] op_sel_hi:[1,0]
	v_add_f32_e32 v134, v134, v135
	v_mov_b32_e32 v135, v134
	s_nop 1
	v_permlane32_swap_b32_e32 v135, v134
	v_add_f32_e32 v134, v134, v135
	v_fmamk_f32 v134, v134, 0x3a800000, v230
	v_mov_b32_e32 v136, v131
	v_mov_b32_e32 v137, v132
	v_mov_b32_e32 v131, v133
	v_pk_add_f32 v[130:131], v[136:137], v[130:131]
	v_rsq_f32_e32 v134, v134
	s_nop 0
	v_add_f32_e32 v130, v130, v131
	v_mov_b32_e32 v131, v130
	s_nop 1
	v_permlane16_swap_b32_e32 v131, v130
	v_pk_mul_f32 v[50:51], v[50:51], v[138:139] op_sel_hi:[1,0]
	v_pk_mul_f32 v[40:41], v[40:41], v[138:139] op_sel_hi:[1,0]
	v_pk_mul_f32 v[38:39], v[38:39], v[138:139] op_sel_hi:[1,0]
	v_add_f32_e32 v130, v130, v131
	v_mov_b32_e32 v131, v130
	s_nop 1
	v_permlane32_swap_b32_e32 v131, v130
	s_waitcnt lgkmcnt(0)
; __device__ __forceinline__ unsigned cvt_pk_bf16(float lo, float hi) { unsigned r; asm volatile("v_cvt_pk_bf16_f32 %0, %1, %2" : "=v"(r) : "v"(lo), "v"(hi)); return r; }
; #define PG8_BAR __builtin_amdgcn_s_barrier()
;     __device__ __forceinline__ void operator()(f32x4 (&acc)[2][2][4][2], const Unit& u, int wr, int wc, int fr, int fq) const {
;     ...
; #pragma unroll
;             for (int ai = 0; ai < 2; ++ai) {
; #pragma unroll
;                 for (int m = 0; m < 4; ++m) { const float rs = rsa[ai][m];
; #pragma unroll
;                     for (int bj = 0; bj < 2; ++bj) { const f32x4 v0 = acc[ai][bj][m][0] * rs, v1 = acc[ai][bj][m][1] * rs;
;                         u32x4 w; w.x = cvt_pk_bf16(v0[0], v0[1]); w.y = cvt_pk_bf16(v0[2], v0[3]); w.z = cvt_pk_bf16(v1[0], v1[1]); w.w = cvt_pk_bf16(v1[2], v1[3]);
;                         *(u32x4*)(rowp + bj * HALF) = w; }
;                     rowp += (size_t)16 * ldr; asm volatile("" : "+v"(rowp) :: "memory"); }
;                 rowp += (size_t)64 * ldr; asm volatile("" : "+v"(rowp)); }
; template <class Epi, class Sched, bool ALIGN_EPI = false, bool SP2 = false>
; __device__ __forceinline__ void gemm_phase(PG8_LAS unsigned char* lds, const Gemm g, const Sched& S, const Epi& E) {
;     ...
;         if constexpr (ALIGN_EPI) { if (wr == 0) PG8_BAR; }
;         if constexpr (!Epi::AFTER_DRAIN) { E(acc, cur, wr, wc, fr, fq); S.done(cur); }
;         if (!has_next) break;
; #pragma unroll
;         for (int a = 0; a < 2; ++a)
; #pragma unroll
;             for (int b = 0; b < 2; ++b)
; #pragma unroll
;                 for (int m = 0; m < 4; ++m)
; #pragma unroll
;                     for (int n = 0; n < 2; ++n) acc[a][b][m][n] = (f32x4){0.f, 0.f, 0.f, 0.f};
;         cur = nxt; cA = nA; cB = nB; ++ui;
;         if constexpr (ALIGN_EPI) { if (wr == 1) PG8_BAR; }
;     }
	v_add_f32_e32 v130, v130, v131
	v_fmamk_f32 v130, v130, 0x3a800000, v230
	s_mov_b64 s[0:1], 0x20000
	v_pk_mul_f32 v[132:133], v[124:125], v[172:173] op_sel_hi:[1,0]
	v_pk_mul_f32 v[124:125], v[122:123], v[172:173] op_sel_hi:[1,0]
	v_cvt_pk_bf16_f32 v122, v126, v127
	v_cvt_pk_bf16_f32 v123, v128, v129
	v_pk_mul_f32 v[34:35], v[34:35], v[134:135] op_sel_hi:[1,0]
	v_cvt_pk_bf16_f32 v124, v124, v125
	v_cvt_pk_bf16_f32 v125, v132, v133
	global_store_dwordx4 v[170:171], v[122:125], off
	v_pk_mul_f32 v[24:25], v[24:25], v[134:135] op_sel_hi:[1,0]
	v_pk_mul_f32 v[22:23], v[22:23], v[134:135] op_sel_hi:[1,0]
	v_pk_mul_f32 v[122:123], v[112:113], v[172:173] op_sel_hi:[1,0]
	v_pk_mul_f32 v[112:113], v[110:111], v[172:173] op_sel_hi:[1,0]
	v_cvt_pk_bf16_f32 v110, v118, v119
	v_cvt_pk_bf16_f32 v111, v120, v121
	v_rsq_f32_e32 v130, v130
	s_nop 0
	v_cvt_pk_bf16_f32 v112, v112, v113
	v_cvt_pk_bf16_f32 v113, v122, v123
	global_store_dwordx4 v[170:171], v[110:113], off offset:256
	v_pk_mul_f32 v[18:19], v[18:19], v[130:131] op_sel_hi:[1,0]
	v_pk_mul_f32 v[8:9], v[8:9], v[130:131] op_sel_hi:[1,0]
	v_lshl_add_u64 v[110:111], v[170:171], 0, s[12:13]
	v_pk_mul_f32 v[112:113], v[116:117], v[154:155] op_sel_hi:[1,0]
	v_pk_mul_f32 v[116:117], v[108:109], v[154:155] op_sel_hi:[1,0]
	v_pk_mul_f32 v[108:109], v[106:107], v[154:155] op_sel_hi:[1,0]
	v_cvt_pk_bf16_f32 v106, v114, v115
	v_cvt_pk_bf16_f32 v107, v112, v113
	v_pk_mul_f32 v[6:7], v[6:7], v[130:131] op_sel_hi:[1,0]
	v_cvt_pk_bf16_f32 v108, v108, v109
	v_cvt_pk_bf16_f32 v109, v116, v117
	global_store_dwordx4 v[110:111], v[106:109], off
	s_andn2_b64 vcc, exec, s[6:7]
	s_nop 0
	v_pk_mul_f32 v[106:107], v[96:97], v[154:155] op_sel_hi:[1,0]
	v_pk_mul_f32 v[96:97], v[94:95], v[154:155] op_sel_hi:[1,0]
	v_cvt_pk_bf16_f32 v94, v102, v103
	v_cvt_pk_bf16_f32 v95, v104, v105
	s_nop 0
	v_cvt_pk_bf16_f32 v96, v96, v97
	v_cvt_pk_bf16_f32 v97, v106, v107
	global_store_dwordx4 v[110:111], v[94:97], off offset:256
	s_nop 1
	v_lshl_add_u64 v[94:95], v[110:111], 0, s[12:13]
	v_pk_mul_f32 v[96:97], v[100:101], v[150:151] op_sel_hi:[1,0]
	v_pk_mul_f32 v[100:101], v[92:93], v[150:151] op_sel_hi:[1,0]
	v_pk_mul_f32 v[92:93], v[90:91], v[150:151] op_sel_hi:[1,0]
	v_cvt_pk_bf16_f32 v90, v98, v99
	v_cvt_pk_bf16_f32 v91, v96, v97
	s_nop 0
	v_cvt_pk_bf16_f32 v92, v92, v93
	v_cvt_pk_bf16_f32 v93, v100, v101
	global_store_dwordx4 v[94:95], v[90:93], off
	s_nop 1
	v_pk_mul_f32 v[90:91], v[80:81], v[150:151] op_sel_hi:[1,0]
	v_pk_mul_f32 v[80:81], v[78:79], v[150:151] op_sel_hi:[1,0]
	v_cvt_pk_bf16_f32 v78, v86, v87
	v_cvt_pk_bf16_f32 v79, v88, v89
	s_nop 0
	v_cvt_pk_bf16_f32 v80, v80, v81
	v_cvt_pk_bf16_f32 v81, v90, v91
	global_store_dwordx4 v[94:95], v[78:81], off offset:256
	s_nop 1
	v_lshl_add_u64 v[78:79], v[94:95], 0, s[12:13]
	v_pk_mul_f32 v[80:81], v[84:85], v[146:147] op_sel_hi:[1,0]
	v_pk_mul_f32 v[84:85], v[76:77], v[146:147] op_sel_hi:[1,0]
	v_pk_mul_f32 v[76:77], v[74:75], v[146:147] op_sel_hi:[1,0]
	v_cvt_pk_bf16_f32 v74, v82, v83
	v_cvt_pk_bf16_f32 v75, v80, v81
	s_nop 0
	v_cvt_pk_bf16_f32 v76, v76, v77
	v_cvt_pk_bf16_f32 v77, v84, v85
	global_store_dwordx4 v[78:79], v[74:77], off
	s_nop 1
	v_pk_mul_f32 v[74:75], v[68:69], v[146:147] op_sel_hi:[1,0]
	v_pk_mul_f32 v[68:69], v[66:67], v[146:147] op_sel_hi:[1,0]
	v_cvt_pk_bf16_f32 v66, v70, v71
	v_cvt_pk_bf16_f32 v67, v72, v73
	s_nop 0
	v_cvt_pk_bf16_f32 v68, v68, v69
	v_cvt_pk_bf16_f32 v69, v74, v75
	global_store_dwordx4 v[78:79], v[66:69], off offset:256
	s_nop 1
	v_lshl_add_u64 v[66:67], v[78:79], 0, s[12:13]
	v_pk_mul_f32 v[68:69], v[60:61], v[142:143] op_sel_hi:[1,0]
	v_lshl_add_u64 v[66:67], v[66:67], 0, s[0:1]
	v_pk_mul_f32 v[60:61], v[58:59], v[142:143] op_sel_hi:[1,0]
	v_cvt_pk_bf16_f32 v58, v62, v63
	v_cvt_pk_bf16_f32 v59, v64, v65
	s_nop 0
	v_cvt_pk_bf16_f32 v60, v60, v61
	v_cvt_pk_bf16_f32 v61, v68, v69
	global_store_dwordx4 v[66:67], v[58:61], off
	s_nop 1
	v_pk_mul_f32 v[58:59], v[48:49], v[142:143] op_sel_hi:[1,0]
	v_pk_mul_f32 v[48:49], v[46:47], v[142:143] op_sel_hi:[1,0]
	v_cvt_pk_bf16_f32 v46, v54, v55
	v_cvt_pk_bf16_f32 v47, v56, v57
	s_nop 0
	v_cvt_pk_bf16_f32 v48, v48, v49
	v_cvt_pk_bf16_f32 v49, v58, v59
	global_store_dwordx4 v[66:67], v[46:49], off offset:256
	s_nop 1
	v_lshl_add_u64 v[46:47], v[66:67], 0, s[12:13]
	v_pk_mul_f32 v[48:49], v[52:53], v[138:139] op_sel_hi:[1,0]
	v_pk_mul_f32 v[52:53], v[44:45], v[138:139] op_sel_hi:[1,0]
	v_pk_mul_f32 v[44:45], v[42:43], v[138:139] op_sel_hi:[1,0]
	v_cvt_pk_bf16_f32 v42, v50, v51
	v_cvt_pk_bf16_f32 v43, v48, v49
	s_nop 0
	v_cvt_pk_bf16_f32 v44, v44, v45
	v_cvt_pk_bf16_f32 v45, v52, v53
	global_store_dwordx4 v[46:47], v[42:45], off
	s_nop 1
	v_pk_mul_f32 v[42:43], v[32:33], v[138:139] op_sel_hi:[1,0]
	v_pk_mul_f32 v[32:33], v[30:31], v[138:139] op_sel_hi:[1,0]
	v_cvt_pk_bf16_f32 v30, v38, v39
	v_cvt_pk_bf16_f32 v31, v40, v41
	s_nop 0
	v_cvt_pk_bf16_f32 v32, v32, v33
	v_cvt_pk_bf16_f32 v33, v42, v43
	global_store_dwordx4 v[46:47], v[30:33], off offset:256
	s_nop 1
	v_lshl_add_u64 v[30:31], v[46:47], 0, s[12:13]
	v_pk_mul_f32 v[32:33], v[36:37], v[134:135] op_sel_hi:[1,0]
	v_pk_mul_f32 v[36:37], v[28:29], v[134:135] op_sel_hi:[1,0]
	v_pk_mul_f32 v[28:29], v[26:27], v[134:135] op_sel_hi:[1,0]
	v_cvt_pk_bf16_f32 v26, v34, v35
	v_cvt_pk_bf16_f32 v27, v32, v33
	s_nop 0
	v_cvt_pk_bf16_f32 v28, v28, v29
	v_cvt_pk_bf16_f32 v29, v36, v37
	global_store_dwordx4 v[30:31], v[26:29], off
	s_nop 1
	v_pk_mul_f32 v[26:27], v[16:17], v[134:135] op_sel_hi:[1,0]
	v_pk_mul_f32 v[16:17], v[14:15], v[134:135] op_sel_hi:[1,0]
	v_cvt_pk_bf16_f32 v14, v22, v23
	v_cvt_pk_bf16_f32 v15, v24, v25
	s_nop 0
	v_cvt_pk_bf16_f32 v16, v16, v17
	v_cvt_pk_bf16_f32 v17, v26, v27
	global_store_dwordx4 v[30:31], v[14:17], off offset:256
	s_nop 1
	v_lshl_add_u64 v[14:15], v[30:31], 0, s[12:13]
	v_pk_mul_f32 v[16:17], v[20:21], v[130:131] op_sel_hi:[1,0]
	v_pk_mul_f32 v[20:21], v[12:13], v[130:131] op_sel_hi:[1,0]
	v_pk_mul_f32 v[12:13], v[10:11], v[130:131] op_sel_hi:[1,0]
	v_cvt_pk_bf16_f32 v10, v18, v19
	v_cvt_pk_bf16_f32 v11, v16, v17
	s_nop 0
	v_cvt_pk_bf16_f32 v12, v12, v13
	v_cvt_pk_bf16_f32 v13, v20, v21
	global_store_dwordx4 v[14:15], v[10:13], off
	s_nop 1
	v_pk_mul_f32 v[10:11], v[4:5], v[130:131] op_sel_hi:[1,0]
	v_pk_mul_f32 v[4:5], v[2:3], v[130:131] op_sel_hi:[1,0]
	v_cvt_pk_bf16_f32 v2, v6, v7
	v_cvt_pk_bf16_f32 v3, v8, v9
	s_nop 0
	v_cvt_pk_bf16_f32 v4, v4, v5
	v_cvt_pk_bf16_f32 v5, v10, v11
	global_store_dwordx4 v[14:15], v[2:5], off offset:256
	s_nop 1
	v_lshl_add_u64 v[2:3], v[14:15], 0, s[12:13]
	s_nop 0
	v_lshl_add_u64 v[2:3], v[2:3], 0, s[0:1]
	s_mov_b64 s[0:1], -1
	s_cbranch_vccnz .LBB0_1116
	s_andn2_b64 vcc, exec, s[4:5]
	s_cbranch_vccnz .LBB0_1115
	s_barrier
	s_branch .LBB0_1115

; __device__ __forceinline__ void load_row_scales(const float* ssp, int row0, int fq, float (&rs)[2][4]) {
;     f32x4 part[2][4];
;     const float* sp = ssp + (size_t)row0 * 16 + 4 * fq;
; #pragma unroll
;     for (int ai = 0; ai < 2; ++ai)
; #pragma unroll
;         for (int m = 0; m < 4; ++m) part[ai][m] = *(const f32x4*)(sp + (size_t)(ai * HALF + m * 16) * 16);
; #pragma unroll
;     for (int ai = 0; ai < 2; ++ai)
; #pragma unroll
;         for (int m = 0; m < 4; ++m) { float t = (part[ai][m][0] + part[ai][m][1]) + (part[ai][m][2] + part[ai][m][3]);
;             t += __shfl_xor(t, 16); t += __shfl_xor(t, 32);
;             rs[ai][m] = 1.0f / sqrtf(t * (1.0f / 1024.0f) + 1e-6f); }
;     __device__ __forceinline__ void operator()(f32x4 (&acc)[2][2][4][2], const Unit& u, int wr, int wc, int fr, int fq) const {
;     ...
;         for (int n = 0; n < 2; ++n) {
;             const int gc0 = u.pn * 128 + wc * 32 + 8 * fq + 4 * n;
;             const float* cwp = cw + gc0; asm volatile("" : "+v"(cwp));
;             const f32x4 wg0 = *(const f32x4*)(cwp), wg1 = *(const f32x4*)(cwp + FF2c), wg2 = *(const f32x4*)(cwp + 2 * FF2c);
;             const f32x4 wv0 = *(const f32x4*)(cwp + FFc), wv1 = *(const f32x4*)(cwp + FF2c + FFc), wv2 = *(const f32x4*)(cwp + 2 * FF2c + FFc);
;             const f32x4 bg = *(const f32x4*)(cb + gc0), bv = *(const f32x4*)(cb + FFc + gc0);
.LBB0_1350:
	s_lshl_b32 s13, s13, 8
	s_add_i32 s13, s13, s24
	v_or_b32_e32 v176, s13, v161
	v_ashrrev_i32_e32 v177, 31, v176
	v_lshlrev_b64 v[130:131], 6, v[176:177]
	v_lshl_add_u64 v[146:147], v[162:163], 0, v[130:131]
	global_load_dwordx4 v[130:133], v[146:147], off
	global_load_dwordx4 v[134:137], v[146:147], off offset:1024
	global_load_dwordx4 v[138:141], v[146:147], off offset:2048
	global_load_dwordx4 v[142:145], v[146:147], off offset:3072
	v_add_co_u32_e32 v168, vcc, 0x2000, v146
	v_mov_b32_e32 v177, v1
	s_nop 0
	v_addc_co_u32_e32 v169, vcc, 0, v147, vcc
	global_load_dwordx4 v[146:149], v[168:169], off
	global_load_dwordx4 v[150:153], v[168:169], off offset:1024
	global_load_dwordx4 v[170:173], v[168:169], off offset:2048
	global_load_dwordx4 v[178:181], v[168:169], off offset:3072
	v_and_b32_e32 v169, 64, v229
	v_xor_b32_e32 v168, 16, v229
	v_add_u32_e32 v169, 64, v169
	v_cmp_lt_i32_e32 vcc, v168, v169
	v_mov_b32_dpp v177, v177 row_ror:1 row_mask:0xf bank_mask:0xf
	v_mov_b32_e32 v189, v177
	v_cndmask_b32_e32 v168, v229, v168, vcc
	v_lshlrev_b32_e32 v174, 2, v168
	v_xor_b32_e32 v168, 32, v229
	v_cmp_lt_i32_e32 vcc, v168, v169
	s_waitcnt vmcnt(0)
	s_mov_b32 s100, 1
	v_mov_b32_e32 v169, v132
	v_cndmask_b32_e32 v168, v229, v168, vcc
	v_lshlrev_b32_e32 v175, 2, v168
	v_mov_b32_e32 v168, v131
	v_mov_b32_e32 v131, v133
	v_pk_add_f32 v[130:131], v[168:169], v[130:131]
	s_nop 0
	v_add_f32_e32 v130, v130, v131
	v_mov_b32_e32 v131, v130
	s_nop 1
	v_permlane16_swap_b32_e32 v131, v130
	s_waitcnt lgkmcnt(0)
	v_add_f32_e32 v130, v130, v131
	v_mov_b32_e32 v131, v130
	s_nop 1
	v_permlane32_swap_b32_e32 v131, v130
	v_add_f32_e32 v130, v130, v131
	v_fmamk_f32 v130, v130, 0x3a800000, v230
	s_ashr_i32 s0, s13, 5
	v_rsq_f32_e32 v168, v130
	s_nop 0
	v_mov_b32_e32 v130, v135
	v_mov_b32_e32 v131, v136
	v_mov_b32_e32 v135, v137
	v_pk_add_f32 v[130:131], v[130:131], v[134:135]
	s_nop 0
	v_add_f32_e32 v130, v130, v131
	v_mov_b32_e32 v131, v130
	s_nop 1
	v_permlane16_swap_b32_e32 v131, v130
	v_add_f32_e32 v205, v130, v131
	v_mov_b32_e32 v130, v139
	v_mov_b32_e32 v131, v140
	v_mov_b32_e32 v139, v141
	v_pk_add_f32 v[130:131], v[130:131], v[138:139]
	ds_bpermute_b32 v206, v175, v205
	v_add_f32_e32 v130, v130, v131
	v_mov_b32_e32 v131, v130
	s_nop 1
	v_permlane16_swap_b32_e32 v131, v130
	v_add_f32_e32 v203, v130, v131
	v_mov_b32_e32 v130, v143
	v_mov_b32_e32 v131, v144
	v_mov_b32_e32 v143, v145
	v_pk_add_f32 v[130:131], v[130:131], v[142:143]
	ds_bpermute_b32 v204, v175, v203
	v_add_f32_e32 v130, v130, v131
	v_mov_b32_e32 v131, v130
	s_nop 1
	v_permlane16_swap_b32_e32 v131, v130
	v_add_f32_e32 v182, v130, v131
	v_mov_b32_e32 v130, v147
	v_mov_b32_e32 v131, v148
	v_mov_b32_e32 v147, v149
	v_pk_add_f32 v[130:131], v[130:131], v[146:147]
	ds_bpermute_b32 v202, v175, v182
	v_add_f32_e32 v130, v130, v131
	v_mov_b32_e32 v131, v130
	s_nop 1
	v_permlane16_swap_b32_e32 v131, v130
	v_add_f32_e32 v244, v130, v131
	v_mov_b32_e32 v130, v151
	v_mov_b32_e32 v131, v152
	v_mov_b32_e32 v151, v153
	v_pk_add_f32 v[130:131], v[130:131], v[150:151]
	ds_bpermute_b32 v245, v175, v244
	v_add_f32_e32 v130, v130, v131
	v_mov_b32_e32 v131, v130
	s_nop 1
	v_permlane16_swap_b32_e32 v131, v130
	v_add_f32_e32 v242, v130, v131
	v_mov_b32_e32 v130, v171
	v_mov_b32_e32 v131, v172
	v_mov_b32_e32 v171, v173
	v_pk_add_f32 v[130:131], v[130:131], v[170:171]
	v_lshl_or_b32 v170, s12, 7, v238
	v_add_f32_e32 v130, v130, v131
	v_mov_b32_e32 v131, v130
	s_nop 1
	v_permlane16_swap_b32_e32 v131, v130
	v_ashrrev_i32_e32 v171, 31, v170
	v_lshlrev_b64 v[150:151], 2, v[170:171]
	v_lshl_add_u64 v[172:173], s[70:71], 0, v[150:151]
	ds_bpermute_b32 v243, v175, v242
	v_add_f32_e32 v240, v130, v131
	v_mov_b32_e32 v130, v179
	v_mov_b32_e32 v131, v180
	v_mov_b32_e32 v179, v181
	v_pk_add_f32 v[130:131], v[130:131], v[178:179]
	ds_bpermute_b32 v241, v175, v240
	v_add_f32_e32 v130, v130, v131
	v_mov_b32_e32 v131, v130
	s_nop 1
	v_permlane16_swap_b32_e32 v131, v130
	v_lshlrev_b64 v[178:179], 1, v[170:171]
	v_add_f32_e32 v169, v130, v131
	v_pk_mul_f32 v[196:197], v[98:99], v[168:169] op_sel_hi:[1,0]
	v_or_b32_e32 v98, s0, v160
	v_mad_i64_i32 v[200:201], s[0:1], v98, s37, 0
	v_pk_mul_f32 v[198:199], v[102:103], v[168:169] op_sel_hi:[1,0]
	v_mov_b64_e32 v[102:103], v[172:173]
	s_movk_i32 s0, 0x5000
	ds_bpermute_b32 v183, v175, v169
	v_add_co_u32_e32 v98, vcc, s0, v102
	s_mov_b32 s0, 0xb000
	s_nop 0
	v_addc_co_u32_e32 v99, vcc, 0, v103, vcc
	global_load_dwordx4 v[142:145], v[98:99], off offset:2048
	v_add_co_u32_e32 v98, vcc, s0, v102
	s_movk_i32 s0, 0x2000
	s_nop 0
	v_addc_co_u32_e32 v99, vcc, 0, v103, vcc
	v_pk_mul_f32 v[194:195], v[104:105], v[168:169] op_sel_hi:[1,0]
	v_add_co_u32_e32 v104, vcc, s0, v102
	v_lshl_add_u64 v[174:175], s[72:73], 0, v[150:151]
	global_load_dwordx4 v[138:141], v[102:103], off
	v_addc_co_u32_e32 v105, vcc, 0, v103, vcc
	s_mov_b32 s0, 0x8000
	global_load_dwordx4 v[146:149], v[174:175], off
	global_load_dwordx4 v[130:133], v[104:105], off offset:3072
	v_add_co_u32_e32 v104, vcc, s0, v102
	v_lshl_add_u64 v[150:151], s[76:77], 0, v[150:151]
	v_pk_mul_f32 v[192:193], v[100:101], v[168:169] op_sel_hi:[1,0]
	global_load_dwordx4 v[98:101], v[98:99], off
	v_addc_co_u32_e32 v105, vcc, 0, v103, vcc
	global_load_dwordx4 v[150:153], v[150:151], off
	s_mov_b32 s0, 0xd000
	global_load_dwordx4 v[134:137], v[104:105], off offset:1024
	v_add_co_u32_e32 v102, vcc, s0, v102
	v_readlane_b32 s0, v253, 44
	s_nop 0
	v_addc_co_u32_e32 v103, vcc, 0, v103, vcc
	global_load_dwordx4 v[102:105], v[102:103], off offset:3072
	v_readlane_b32 s1, v253, 45
	v_mov_b32_dpp v189, v196 row_shr:1 row_mask:0xf bank_mask:0xf
	s_nop 0
	v_lshl_add_u64 v[180:181], v[200:201], 1, s[0:1]
	v_lshl_add_u64 v[184:185], v[180:181], 0, v[178:179]
	v_mov_b32_e32 v181, v1
	v_mov_b32_e32 v180, v177
	s_nop 0
	v_mov_b32_dpp v181, v181 row_ror:2 row_mask:0xf bank_mask:0xf
	v_mov_b32_e32 v188, v181
	v_mov_b32_dpp v180, v198 row_shr:1 row_mask:0xf bank_mask:0xf
	v_mov_b32_e32 v190, v181
	v_mov_b32_dpp v188, v198 row_shr:2 row_mask:0xf bank_mask:0xf
	v_mov_b32_e32 v191, v181
	v_mov_b32_dpp v190, v196 row_shr:2 row_mask:0xf bank_mask:0xf
	v_mov_b32_e32 v207, v181
	v_mov_b32_dpp v191, v197 row_shr:2 row_mask:0xf bank_mask:0xf
	s_waitcnt vmcnt(0) lgkmcnt(0)
; __device__ __forceinline__ unsigned cvt_pk_bf16(float lo, float hi) { unsigned r; asm volatile("v_cvt_pk_bf16_f32 %0, %1, %2" : "=v"(r) : "v"(lo), "v"(hi)); return r; }
;     __device__ __forceinline__ void operator()(f32x4 (&acc)[2][2][4][2], const Unit& u, int wr, int wc, int fr, int fq) const {
;     ...
; #pragma unroll
;             for (int ai = 0; ai < 2; ++ai) {
; #pragma unroll
;                 for (int m = 0; m < 4; ++m) {
;                     float og[4];
; #pragma unroll
;                     for (int j = 0; j < 4; ++j) {
;                         const float vg = acc[ai][0][m][n][j], vv = acc[ai][1][m][n][j];
;                         const float pg = (m > 0) ? acc[ai][0][m - 1][n][j] : 0.f, pv = (m > 0) ? acc[ai][1][m - 1][n][j] : 0.f;
;                         const float g1 = dppf(dppf(0.f, pg, 2), vg, 0), g2 = dppf(dppf(0.f, pg, 3), vg, 1);
;                         const float v1 = dppf(dppf(0.f, pv, 2), vv, 0), v2 = dppf(dppf(0.f, pv, 3), vv, 1);
;                         const float cgate = bg[j] + wg0[j] * g2 + wg1[j] * g1 + wg2[j] * vg;
;                         const float cval = bv[j] + wv0[j] * v2 + wv1[j] * v1 + wv2[j] * vv;
;                         og[j] = cgate * __builtin_amdgcn_rcpf(1.0f + __builtin_amdgcn_exp2f(-1.4426950408889634f * cgate)) * cval; }
;                     const unsigned long long w = (unsigned long long)cvt_pk_bf16(og[0], og[1]) | ((unsigned long long)cvt_pk_bf16(og[2], og[3]) << 32);
;                     if (m == 0) {
;                         if (fr >= 2) *(unsigned long long*)gp = w;
;                         else { *(unsigned long long*)sb = (unsigned long long)cvt_pk_bf16(acc[ai][0][0][n][0], acc[ai][0][0][n][1]) | ((unsigned long long)cvt_pk_bf16(acc[ai][0][0][n][2], acc[ai][0][0][n][3]) << 32);
;                                *(unsigned long long*)(sb + FFc) = (unsigned long long)cvt_pk_bf16(acc[ai][1][0][n][0], acc[ai][1][0][n][1]) | ((unsigned long long)cvt_pk_bf16(acc[ai][1][0][n][2], acc[ai][1][0][n][3]) << 32); }
	v_fma_f32 v188, v138, v188, v146
	v_fmac_f32_e32 v188, v142, v180
	v_mov_b32_dpp v207, v192 row_shr:2 row_mask:0xf bank_mask:0xf
	v_fmac_f32_e32 v188, v198, v98
	v_fma_f32 v180, v130, v190, v150
	v_mov_b32_e32 v190, v177
	v_fmac_f32_e32 v180, v134, v189
	v_mul_f32_e32 v189, 0xbfb8aa3b, v188
	v_exp_f32_e32 v189, v189
	v_mov_b32_dpp v190, v197 row_shr:1 row_mask:0xf bank_mask:0xf
	v_add_f32_e32 v189, 1.0, v189
	v_rcp_f32_e32 v189, v189
	v_fmac_f32_e32 v180, v196, v102
	v_mul_f32_e32 v188, v188, v189
	v_mov_b32_e32 v189, v181
	v_mul_f32_e32 v180, v180, v188
	v_mov_b32_e32 v188, v177
	v_mov_b32_dpp v189, v199 row_shr:2 row_mask:0xf bank_mask:0xf
	v_fma_f32 v189, v139, v189, v147
	v_mov_b32_dpp v188, v199 row_shr:1 row_mask:0xf bank_mask:0xf
	v_fmac_f32_e32 v189, v143, v188
	v_fmac_f32_e32 v189, v199, v99
	v_fma_f32 v188, v131, v191, v151
	v_fmac_f32_e32 v188, v135, v190
	v_mul_f32_e32 v190, 0xbfb8aa3b, v189
	v_exp_f32_e32 v190, v190
	v_fmac_f32_e32 v188, v197, v103
	v_mov_b32_e32 v191, v177
	v_add_f32_e32 v190, 1.0, v190
	v_rcp_f32_e32 v190, v190
	v_mov_b32_dpp v191, v192 row_shr:1 row_mask:0xf bank_mask:0xf
	v_mul_f32_e32 v189, v189, v190
	v_mov_b32_e32 v190, v181
	v_mul_f32_e32 v188, v188, v189
	v_mov_b32_e32 v189, v177
	v_mov_b32_dpp v190, v194 row_shr:2 row_mask:0xf bank_mask:0xf
	v_fma_f32 v190, v140, v190, v148
	v_mov_b32_dpp v189, v194 row_shr:1 row_mask:0xf bank_mask:0xf
	v_fmac_f32_e32 v190, v144, v189
	v_fmac_f32_e32 v190, v194, v100
	v_fma_f32 v189, v132, v207, v152
	v_fmac_f32_e32 v189, v136, v191
	v_mul_f32_e32 v191, 0xbfb8aa3b, v190
	v_exp_f32_e32 v191, v191
	v_fmac_f32_e32 v189, v192, v104
	v_cvt_pk_bf16_f32 v180, v180, v188
	v_add_f32_e32 v191, 1.0, v191
	v_rcp_f32_e32 v191, v191
	s_nop 0
	v_mul_f32_e32 v190, v190, v191
	v_mov_b32_e32 v191, v181
	v_mul_f32_e32 v189, v189, v190
	v_mov_b32_e32 v190, v177
	v_mov_b32_dpp v191, v195 row_shr:2 row_mask:0xf bank_mask:0xf
	v_fma_f32 v191, v141, v191, v149
	v_mov_b32_dpp v190, v195 row_shr:1 row_mask:0xf bank_mask:0xf
	v_mov_b32_dpp v181, v193 row_shr:2 row_mask:0xf bank_mask:0xf
	v_fmac_f32_e32 v191, v145, v190
	v_mov_b32_dpp v177, v193 row_shr:1 row_mask:0xf bank_mask:0xf
	v_fmac_f32_e32 v191, v195, v101
	v_fma_f32 v181, v133, v181, v153
	v_fmac_f32_e32 v181, v137, v177
	v_mul_f32_e32 v177, 0xbfb8aa3b, v191
	v_exp_f32_e32 v177, v177
	v_fmac_f32_e32 v181, v193, v105
	v_add_f32_e32 v177, 1.0, v177
	v_rcp_f32_e32 v177, v177
	s_nop 0
	v_mul_f32_e32 v177, v191, v177
	v_mul_f32_e32 v177, v181, v177
	v_cvt_pk_bf16_f32 v181, v189, v177
	s_and_saveexec_b64 s[0:1], s[6:7]
	s_xor_b64 s[0:1], exec, s[0:1]
	s_mov_b64 s[50:51], 0x16000
	s_mov_b64 s[52:53], 0x58000
	s_mov_b64 s[54:55], 0xb000
	s_cbranch_execz .LBB0_1352
	v_cvt_pk_bf16_f32 v180, v198, v199
	v_cvt_pk_bf16_f32 v181, v194, v195
	v_add_co_u32_e32 v188, vcc, 0x1000, v184
	global_store_dwordx2 v[184:185], v[180:181], off
	v_cvt_pk_bf16_f32 v180, v196, v197
	v_cvt_pk_bf16_f32 v181, v192, v193
	s_nop 0
	v_addc_co_u32_e32 v189, vcc, 0, v185, vcc
	global_store_dwordx2 v[188:189], v[180:181], off offset:1536
